# GEMM K-loop heads: first four ds_read_b128 of the load segment issued ahead of the scalar pointer arithmetic/selects (7.2)
# baseline (speedup 1.0000x reference)
; #define PG8_STAGE(bufoff, gbase, voff) do { _Pragma("unroll") for (int _i = 0; _i < 2; ++_i) \
;         __builtin_amdgcn_global_load_lds((const unsigned*)((const char*)(gbase) + (voff)[_i]), (PG8_LAS unsigned*)(lds + (bufoff) + ldsw + _i * 8192), 16, 0, 0); } while (0)
; #define PG8_LDA(dst, b, h) do { _Pragma("unroll") for (int m = 0; m < 4; ++m) _Pragma("unroll") for (int k = 0; k < 2; ++k) dst[m][k] = *(const PG8_LAS bf16x8*)(lds + PG8_SA(b, h) + aoff + m * 2048 + k * 1024); } while (0)
; #define PG8_LDB(dst, b, h) do { _Pragma("unroll") for (int n = 0; n < 2; ++n) _Pragma("unroll") for (int k = 0; k < 2; ++k) dst[n][k] = *(const PG8_LAS bf16x8*)(lds + PG8_SB(b, h) + boff + n * 2048 + k * 1024); } while (0)
; #define PG8_MMA(ai, bj, At, Bt) do { __builtin_amdgcn_s_setprio(1); _Pragma("unroll") for (int m = 0; m < 4; ++m) _Pragma("unroll") for (int n = 0; n < 2; ++n) _Pragma("unroll") for (int k = 0; k < 2; ++k) \
;         acc[ai][bj][m][n] = __builtin_amdgcn_mfma_f32_16x16x32_bf16(Bt[n][k], At[m][k], acc[ai][bj][m][n], 0, 0, 0); __builtin_amdgcn_s_setprio(0); } while (0)
; #define PG8_WAIT_V(n) asm volatile("s_waitcnt vmcnt(" #n ")" ::: "memory")
; #define PG8_WAIT_L(n) asm volatile("s_waitcnt lgkmcnt(" #n ")" ::: "memory")
; #define PG8_BAR __builtin_amdgcn_s_barrier()
; template <class Epi, class Sched, bool ALIGN_EPI = false, bool SP2 = false, bool UNIFORM_NT = false>
; __device__ __forceinline__ void gemm_phase(PG8_LAS unsigned char* lds, const Gemm g, const Sched& S, const Epi& E, int tid_in) {
;     ...
;             const char* a1 = cA + (size_t)(t + 1) * kstep;
;             const char* a2 = last ? nA : cA + (size_t)(t + 2) * kstep; const char* b2 = last ? nB : cB + (size_t)(t + 2) * kstep;
;             const char* a3 = a2 + kstep; const char* b3 = b2 + kstep;
;             if (last && has_next) S.a_ready(nxt);
;             if constexpr (SP2) {
;             PG8_LDB(B0, 0, 0); PG8_LDB(B1, 0, 1); PG8_SCHED; PG8_LDA(At, 0, 0); PG8_STAGE(PG8_SA(1, 1), a1 + hstepA, voffA);
;             PG8_WAIT_V(8); PG8_WAIT_L(0); PG8_BAR; PG8_MMA(0, 0, At, B0); PG8_MMA(0, 1, At, B1); PG8_BAR; PG8_SCHED;
;             PG8_LDA(At, 0, 1); PG8_STAGE(PG8_SB(0, 0), b2, voffB); PG8_STAGE(PG8_SB(0, 1), b2 + hstepB, voffB); PG8_STAGE(PG8_SA(0, 0), a2, voffA);
;             PG8_WAIT_V(8); PG8_WAIT_L(0); PG8_BAR; PG8_MMA(1, 0, At, B0); PG8_MMA(1, 1, At, B1); PG8_BAR; PG8_SCHED;
.LBB0_54:
	s_add_i32 s49, 0, 0x10000
	v_add_u32_e32 v140, s49, v143
	ds_read_b128 v[146:149], v140
	ds_read_b128 v[150:153], v140 offset:1024
	ds_read_b128 v[154:157], v140 offset:2048
	ds_read_b128 v[158:161], v140 offset:3072
	s_add_u32 s47, s54, 0xfffc0080
	s_addc_u32 s48, s55, -1
	s_cmp_eq_u32 s46, 12
	s_cselect_b32 s59, s12, s48
	s_cselect_b32 s58, s13, s47
	s_cselect_b32 s57, s31, s45
	s_cselect_b32 s56, s35, s43
	s_add_i32 s47, 0, 0x14000
	v_add_u32_e32 v140, s47, v143
	ds_read_b128 v[162:165], v140
	ds_read_b128 v[166:169], v140 offset:1024
	ds_read_b128 v[170:173], v140 offset:2048
	ds_read_b128 v[174:177], v140 offset:3072
	v_lshl_add_u64 v[140:141], s[54:55], 0, v[136:137]
	s_add_i32 m0, s7, 0xc000
	ds_read_b128 v[178:181], v145
	ds_read_b128 v[182:185], v145 offset:1024
	ds_read_b128 v[186:189], v145 offset:2048
	ds_read_b128 v[190:193], v145 offset:3072
	ds_read_b128 v[194:197], v145 offset:4096
	ds_read_b128 v[198:201], v145 offset:5120
	ds_read_b128 v[202:205], v145 offset:6144
	ds_read_b128 v[206:209], v145 offset:7168
	global_load_lds_dwordx4 v[140:141], off
	v_lshl_add_u64 v[140:141], s[54:55], 0, v[138:139]
	s_add_i32 m0, s7, 0xe000
	s_nop 0
	global_load_lds_dwordx4 v[140:141], off
	s_waitcnt vmcnt(8)
	s_waitcnt lgkmcnt(0)
	s_barrier
	s_setprio 1
	s_waitcnt lgkmcnt(0)
	v_mfma_f32_16x16x32_bf16 v[126:129], v[146:149], v[178:181], v[126:129]
	v_mfma_f32_16x16x32_bf16 v[122:125], v[154:157], v[178:181], v[122:125]
	v_mfma_f32_16x16x32_bf16 v[110:113], v[146:149], v[186:189], v[110:113]
	v_mfma_f32_16x16x32_bf16 v[106:109], v[154:157], v[186:189], v[106:109]
	v_mfma_f32_16x16x32_bf16 v[94:97], v[146:149], v[194:197], v[94:97]
	v_mfma_f32_16x16x32_bf16 v[90:93], v[154:157], v[194:197], v[90:93]
	v_mfma_f32_16x16x32_bf16 v[78:81], v[146:149], v[202:205], v[78:81]
	v_mfma_f32_16x16x32_bf16 v[74:77], v[154:157], v[202:205], v[74:77]
	v_mfma_f32_16x16x32_bf16 v[126:129], v[150:153], v[182:185], v[126:129]
	v_mfma_f32_16x16x32_bf16 v[122:125], v[158:161], v[182:185], v[122:125]
	v_mfma_f32_16x16x32_bf16 v[110:113], v[150:153], v[190:193], v[110:113]
	v_mfma_f32_16x16x32_bf16 v[106:109], v[158:161], v[190:193], v[106:109]
	v_mfma_f32_16x16x32_bf16 v[94:97], v[150:153], v[198:201], v[94:97]
	v_mfma_f32_16x16x32_bf16 v[90:93], v[158:161], v[198:201], v[90:93]
	v_mfma_f32_16x16x32_bf16 v[78:81], v[150:153], v[206:209], v[78:81]
	v_mfma_f32_16x16x32_bf16 v[74:77], v[158:161], v[206:209], v[74:77]
	s_setprio 0
	s_setprio 1
	v_mfma_f32_16x16x32_bf16 v[118:121], v[162:165], v[178:181], v[118:121]
	v_mfma_f32_16x16x32_bf16 v[114:117], v[170:173], v[178:181], v[114:117]
	v_mfma_f32_16x16x32_bf16 v[102:105], v[162:165], v[186:189], v[102:105]
	v_mfma_f32_16x16x32_bf16 v[98:101], v[170:173], v[186:189], v[98:101]
	v_mfma_f32_16x16x32_bf16 v[86:89], v[162:165], v[194:197], v[86:89]
	v_mfma_f32_16x16x32_bf16 v[82:85], v[170:173], v[194:197], v[82:85]
	v_mfma_f32_16x16x32_bf16 v[70:73], v[162:165], v[202:205], v[70:73]
	v_mfma_f32_16x16x32_bf16 v[66:69], v[170:173], v[202:205], v[66:69]
	v_mfma_f32_16x16x32_bf16 v[118:121], v[166:169], v[182:185], v[118:121]
	v_mfma_f32_16x16x32_bf16 v[114:117], v[174:177], v[182:185], v[114:117]
	v_mfma_f32_16x16x32_bf16 v[102:105], v[166:169], v[190:193], v[102:105]
	v_mfma_f32_16x16x32_bf16 v[98:101], v[174:177], v[190:193], v[98:101]
	v_mfma_f32_16x16x32_bf16 v[86:89], v[166:169], v[198:201], v[86:89]
	v_mfma_f32_16x16x32_bf16 v[82:85], v[174:177], v[198:201], v[82:85]
	v_mfma_f32_16x16x32_bf16 v[70:73], v[166:169], v[206:209], v[70:73]
	v_mfma_f32_16x16x32_bf16 v[66:69], v[174:177], v[206:209], v[66:69]
	s_setprio 0
	s_barrier
	s_add_i32 s48, s49, s0
	v_lshl_add_u64 v[140:141], s[56:57], 0, v[0:1]
	s_mov_b32 m0, s48
	ds_read_b128 v[178:181], v145 offset:16384
	ds_read_b128 v[182:185], v145 offset:17408
	ds_read_b128 v[186:189], v145 offset:18432
	ds_read_b128 v[190:193], v145 offset:19456
	ds_read_b128 v[194:197], v145 offset:20480
	ds_read_b128 v[198:201], v145 offset:21504
	ds_read_b128 v[202:205], v145 offset:22528
	ds_read_b128 v[206:209], v145 offset:23552
	global_load_lds_dwordx4 v[140:141], off
	s_add_i32 m0, s48, 0x2000
	s_add_u32 s48, s56, 0x40000
	v_lshl_add_u64 v[210:211], s[56:57], 0, v[130:131]
	s_addc_u32 s49, s57, 0
	s_add_i32 s47, s47, s0
	global_load_lds_dwordx4 v[210:211], off
	v_lshl_add_u64 v[212:213], s[48:49], 0, v[0:1]
	s_mov_b32 m0, s47
	v_lshl_add_u64 v[214:215], s[58:59], 0, v[132:133]
	global_load_lds_dwordx4 v[212:213], off
	v_lshl_add_u64 v[212:213], s[48:49], 0, v[130:131]
	s_add_i32 m0, s47, 0x2000
	s_nop 0
	global_load_lds_dwordx4 v[212:213], off
	v_lshl_add_u64 v[212:213], s[58:59], 0, v[134:135]
	s_mov_b32 m0, s7
	s_nop 0
	global_load_lds_dwordx4 v[212:213], off
	s_mov_b32 m0, s8
	s_nop 0
	global_load_lds_dwordx4 v[214:215], off
	s_waitcnt vmcnt(8)
	s_waitcnt lgkmcnt(0)
	s_barrier
; #define PG8_STAGE(bufoff, gbase, voff) do { _Pragma("unroll") for (int _i = 0; _i < 2; ++_i) \
;         __builtin_amdgcn_global_load_lds((const unsigned*)((const char*)(gbase) + (voff)[_i]), (PG8_LAS unsigned*)(lds + (bufoff) + ldsw + _i * 8192), 16, 0, 0); } while (0)
; #define PG8_LDA(dst, b, h) do { _Pragma("unroll") for (int m = 0; m < 4; ++m) _Pragma("unroll") for (int k = 0; k < 2; ++k) dst[m][k] = *(const PG8_LAS bf16x8*)(lds + PG8_SA(b, h) + aoff + m * 2048 + k * 1024); } while (0)
; #define PG8_LDB(dst, b, h) do { _Pragma("unroll") for (int n = 0; n < 2; ++n) _Pragma("unroll") for (int k = 0; k < 2; ++k) dst[n][k] = *(const PG8_LAS bf16x8*)(lds + PG8_SB(b, h) + boff + n * 2048 + k * 1024); } while (0)
; #define PG8_MMA(ai, bj, At, Bt) do { __builtin_amdgcn_s_setprio(1); _Pragma("unroll") for (int m = 0; m < 4; ++m) _Pragma("unroll") for (int n = 0; n < 2; ++n) _Pragma("unroll") for (int k = 0; k < 2; ++k) \
;         acc[ai][bj][m][n] = __builtin_amdgcn_mfma_f32_16x16x32_bf16(Bt[n][k], At[m][k], acc[ai][bj][m][n], 0, 0, 0); __builtin_amdgcn_s_setprio(0); } while (0)
; #define PG8_WAIT_V(n) asm volatile("s_waitcnt vmcnt(" #n ")" ::: "memory")
; #define PG8_WAIT_L(n) asm volatile("s_waitcnt lgkmcnt(" #n ")" ::: "memory")
; #define PG8_BAR __builtin_amdgcn_s_barrier()
; #define PG8_SCHED __builtin_amdgcn_sched_barrier(0)
; template <class Epi, class Sched, bool ALIGN_EPI = false, bool SP2 = false, bool UNIFORM_NT = false>
; __device__ __forceinline__ void gemm_phase(PG8_LAS unsigned char* lds, const Gemm g, const Sched& S, const Epi& E, int tid_in) {
;     ...
;             PG8_WAIT_V(8); PG8_WAIT_L(0); PG8_BAR; PG8_MMA(1, 0, At, B0); PG8_MMA(1, 1, At, B1); PG8_BAR; PG8_SCHED;
;             PG8_LDB(B0, 1, 0); PG8_LDB(B1, 1, 1); PG8_SCHED; PG8_LDA(At, 1, 0); PG8_STAGE(PG8_SA(0, 1), a2 + hstepA, voffA);
;             PG8_WAIT_V(8); PG8_WAIT_L(0); PG8_BAR; PG8_MMA(0, 0, At, B0); PG8_MMA(0, 1, At, B1); PG8_BAR; PG8_SCHED;
	s_setprio 1
	s_waitcnt lgkmcnt(0)
	v_mfma_f32_16x16x32_bf16 v[62:65], v[146:149], v[178:181], v[62:65]
	v_mfma_f32_16x16x32_bf16 v[58:61], v[154:157], v[178:181], v[58:61]
	v_mfma_f32_16x16x32_bf16 v[46:49], v[146:149], v[186:189], v[46:49]
	v_mfma_f32_16x16x32_bf16 v[42:45], v[154:157], v[186:189], v[42:45]
	v_mfma_f32_16x16x32_bf16 v[30:33], v[146:149], v[194:197], v[30:33]
	v_mfma_f32_16x16x32_bf16 v[26:29], v[154:157], v[194:197], v[26:29]
	v_mfma_f32_16x16x32_bf16 v[14:17], v[146:149], v[202:205], v[14:17]
	v_mfma_f32_16x16x32_bf16 v[10:13], v[154:157], v[202:205], v[10:13]
	v_mfma_f32_16x16x32_bf16 v[62:65], v[150:153], v[182:185], v[62:65]
	v_mfma_f32_16x16x32_bf16 v[58:61], v[158:161], v[182:185], v[58:61]
	v_mfma_f32_16x16x32_bf16 v[46:49], v[150:153], v[190:193], v[46:49]
	v_mfma_f32_16x16x32_bf16 v[42:45], v[158:161], v[190:193], v[42:45]
	v_mfma_f32_16x16x32_bf16 v[30:33], v[150:153], v[198:201], v[30:33]
	v_mfma_f32_16x16x32_bf16 v[26:29], v[158:161], v[198:201], v[26:29]
	v_mfma_f32_16x16x32_bf16 v[14:17], v[150:153], v[206:209], v[14:17]
	v_mfma_f32_16x16x32_bf16 v[10:13], v[158:161], v[206:209], v[10:13]
	s_setprio 0
	s_setprio 1
	v_mfma_f32_16x16x32_bf16 v[54:57], v[162:165], v[178:181], v[54:57]
	v_mfma_f32_16x16x32_bf16 v[50:53], v[170:173], v[178:181], v[50:53]
	v_mfma_f32_16x16x32_bf16 v[38:41], v[162:165], v[186:189], v[38:41]
	v_mfma_f32_16x16x32_bf16 v[34:37], v[170:173], v[186:189], v[34:37]
	v_mfma_f32_16x16x32_bf16 v[22:25], v[162:165], v[194:197], v[22:25]
	v_mfma_f32_16x16x32_bf16 v[18:21], v[170:173], v[194:197], v[18:21]
	v_mfma_f32_16x16x32_bf16 v[6:9], v[162:165], v[202:205], v[6:9]
	v_mfma_f32_16x16x32_bf16 v[2:5], v[170:173], v[202:205], v[2:5]
	v_mfma_f32_16x16x32_bf16 v[54:57], v[166:169], v[182:185], v[54:57]
	v_mfma_f32_16x16x32_bf16 v[50:53], v[174:177], v[182:185], v[50:53]
	v_mfma_f32_16x16x32_bf16 v[38:41], v[166:169], v[190:193], v[38:41]
	v_mfma_f32_16x16x32_bf16 v[34:37], v[174:177], v[190:193], v[34:37]
	v_mfma_f32_16x16x32_bf16 v[22:25], v[166:169], v[198:201], v[22:25]
	v_mfma_f32_16x16x32_bf16 v[18:21], v[174:177], v[198:201], v[18:21]
	v_mfma_f32_16x16x32_bf16 v[6:9], v[166:169], v[206:209], v[6:9]
	v_mfma_f32_16x16x32_bf16 v[2:5], v[174:177], v[206:209], v[2:5]
	s_setprio 0
	s_barrier
	s_add_i32 s47, 0, 0x18000
	s_add_i32 s52, 0, 0x1c000
	v_add_u32_e32 v158, s47, v143
	v_add_u32_e32 v174, s52, v143
	ds_read_b128 v[146:149], v158
	ds_read_b128 v[150:153], v158 offset:1024
	ds_read_b128 v[154:157], v158 offset:2048
	ds_read_b128 v[158:161], v158 offset:3072
	ds_read_b128 v[162:165], v174
	ds_read_b128 v[166:169], v174 offset:1024
	ds_read_b128 v[170:173], v174 offset:2048
	ds_read_b128 v[174:177], v174 offset:3072
	s_add_u32 s48, s58, 0x40000
	s_addc_u32 s49, s59, 0
	s_mov_b32 m0, s9
	v_lshl_add_u64 v[216:217], s[48:49], 0, v[134:135]
	ds_read_b128 v[178:181], v145 offset:32768
	ds_read_b128 v[182:185], v145 offset:33792
	ds_read_b128 v[186:189], v145 offset:34816
	ds_read_b128 v[190:193], v145 offset:35840
	ds_read_b128 v[194:197], v145 offset:36864
	ds_read_b128 v[198:201], v145 offset:37888
	ds_read_b128 v[202:205], v145 offset:38912
	ds_read_b128 v[206:209], v145 offset:39936
	global_load_lds_dwordx4 v[216:217], off
	v_lshl_add_u64 v[216:217], s[48:49], 0, v[132:133]
	s_mov_b32 m0, s14
	s_nop 0
	global_load_lds_dwordx4 v[216:217], off
	s_waitcnt vmcnt(8)
	s_waitcnt lgkmcnt(0)
	s_barrier
	s_setprio 1
	s_waitcnt lgkmcnt(0)
	v_mfma_f32_16x16x32_bf16 v[126:129], v[146:149], v[178:181], v[126:129]
	v_mfma_f32_16x16x32_bf16 v[122:125], v[154:157], v[178:181], v[122:125]
	v_mfma_f32_16x16x32_bf16 v[110:113], v[146:149], v[186:189], v[110:113]
	v_mfma_f32_16x16x32_bf16 v[106:109], v[154:157], v[186:189], v[106:109]
	v_mfma_f32_16x16x32_bf16 v[94:97], v[146:149], v[194:197], v[94:97]
	v_mfma_f32_16x16x32_bf16 v[90:93], v[154:157], v[194:197], v[90:93]
	v_mfma_f32_16x16x32_bf16 v[78:81], v[146:149], v[202:205], v[78:81]
	v_mfma_f32_16x16x32_bf16 v[74:77], v[154:157], v[202:205], v[74:77]
	v_mfma_f32_16x16x32_bf16 v[126:129], v[150:153], v[182:185], v[126:129]
	v_mfma_f32_16x16x32_bf16 v[122:125], v[158:161], v[182:185], v[122:125]
	v_mfma_f32_16x16x32_bf16 v[110:113], v[150:153], v[190:193], v[110:113]
	v_mfma_f32_16x16x32_bf16 v[106:109], v[158:161], v[190:193], v[106:109]
	v_mfma_f32_16x16x32_bf16 v[94:97], v[150:153], v[198:201], v[94:97]
	v_mfma_f32_16x16x32_bf16 v[90:93], v[158:161], v[198:201], v[90:93]
	v_mfma_f32_16x16x32_bf16 v[78:81], v[150:153], v[206:209], v[78:81]
	v_mfma_f32_16x16x32_bf16 v[74:77], v[158:161], v[206:209], v[74:77]
	s_setprio 0
	s_setprio 1
	v_mfma_f32_16x16x32_bf16 v[118:121], v[162:165], v[178:181], v[118:121]
	v_mfma_f32_16x16x32_bf16 v[114:117], v[170:173], v[178:181], v[114:117]
	v_mfma_f32_16x16x32_bf16 v[102:105], v[162:165], v[186:189], v[102:105]
	v_mfma_f32_16x16x32_bf16 v[98:101], v[170:173], v[186:189], v[98:101]
	v_mfma_f32_16x16x32_bf16 v[86:89], v[162:165], v[194:197], v[86:89]
	v_mfma_f32_16x16x32_bf16 v[82:85], v[170:173], v[194:197], v[82:85]
	v_mfma_f32_16x16x32_bf16 v[70:73], v[162:165], v[202:205], v[70:73]
	v_mfma_f32_16x16x32_bf16 v[66:69], v[170:173], v[202:205], v[66:69]
	v_mfma_f32_16x16x32_bf16 v[118:121], v[166:169], v[182:185], v[118:121]
	v_mfma_f32_16x16x32_bf16 v[114:117], v[174:177], v[182:185], v[114:117]
	v_mfma_f32_16x16x32_bf16 v[102:105], v[166:169], v[190:193], v[102:105]
	v_mfma_f32_16x16x32_bf16 v[98:101], v[174:177], v[190:193], v[98:101]
	v_mfma_f32_16x16x32_bf16 v[86:89], v[166:169], v[198:201], v[86:89]
	v_mfma_f32_16x16x32_bf16 v[82:85], v[174:177], v[198:201], v[82:85]
	v_mfma_f32_16x16x32_bf16 v[70:73], v[166:169], v[206:209], v[70:73]
	v_mfma_f32_16x16x32_bf16 v[66:69], v[174:177], v[206:209], v[66:69]
	s_setprio 0
	s_barrier
; #define PG8_STAGE(bufoff, gbase, voff) do { _Pragma("unroll") for (int _i = 0; _i < 2; ++_i) \
;         __builtin_amdgcn_global_load_lds((const unsigned*)((const char*)(gbase) + (voff)[_i]), (PG8_LAS unsigned*)(lds + (bufoff) + ldsw + _i * 8192), 16, 0, 0); } while (0)
; #define PG8_LDA(dst, b, h) do { _Pragma("unroll") for (int m = 0; m < 4; ++m) _Pragma("unroll") for (int k = 0; k < 2; ++k) dst[m][k] = *(const PG8_LAS bf16x8*)(lds + PG8_SA(b, h) + aoff + m * 2048 + k * 1024); } while (0)
; #define PG8_MMA(ai, bj, At, Bt) do { __builtin_amdgcn_s_setprio(1); _Pragma("unroll") for (int m = 0; m < 4; ++m) _Pragma("unroll") for (int n = 0; n < 2; ++n) _Pragma("unroll") for (int k = 0; k < 2; ++k) \
;         acc[ai][bj][m][n] = __builtin_amdgcn_mfma_f32_16x16x32_bf16(Bt[n][k], At[m][k], acc[ai][bj][m][n], 0, 0, 0); __builtin_amdgcn_s_setprio(0); } while (0)
; #define PG8_WAIT_V(n) asm volatile("s_waitcnt vmcnt(" #n ")" ::: "memory")
; #define PG8_WAIT_L(n) asm volatile("s_waitcnt lgkmcnt(" #n ")" ::: "memory")
; #define PG8_BAR __builtin_amdgcn_s_barrier()
; #define PG8_SCHED __builtin_amdgcn_sched_barrier(0)
; template <class Epi, class Sched, bool ALIGN_EPI = false, bool SP2 = false, bool UNIFORM_NT = false>
; __device__ __forceinline__ void gemm_phase(PG8_LAS unsigned char* lds, const Gemm g, const Sched& S, const Epi& E, int tid_in) {
;     ...
;             PG8_LDA(At, 1, 1); PG8_STAGE(PG8_SB(1, 0), b3, voffB); PG8_STAGE(PG8_SB(1, 1), b3 + hstepB, voffB); PG8_STAGE(PG8_SA(1, 0), a3, voffA);
;             PG8_WAIT_V(8); PG8_WAIT_L(0); PG8_BAR; PG8_MMA(1, 0, At, B0); PG8_MMA(1, 1, At, B1); PG8_BAR; PG8_SCHED;
	s_add_i32 s47, s47, s0
	v_lshl_add_u64 v[140:141], v[140:141], 0, s[82:83]
	s_mov_b32 m0, s47
	ds_read_b128 v[178:181], v145 offset:49152
	ds_read_b128 v[182:185], v145 offset:50176
	ds_read_b128 v[186:189], v145 offset:51200
	ds_read_b128 v[190:193], v145 offset:52224
	ds_read_b128 v[194:197], v145 offset:53248
	ds_read_b128 v[198:201], v145 offset:54272
	ds_read_b128 v[202:205], v145 offset:55296
	ds_read_b128 v[206:209], v145 offset:56320
	global_load_lds_dwordx4 v[140:141], off
	s_add_i32 m0, s47, 0x2000
	s_add_u32 s48, s56, 0x40080
	v_lshl_add_u64 v[140:141], v[210:211], 0, s[82:83]
	s_addc_u32 s49, s57, 0
	s_add_i32 s47, s52, s0
	global_load_lds_dwordx4 v[140:141], off
	v_lshl_add_u64 v[140:141], s[48:49], 0, v[0:1]
	s_mov_b32 m0, s47
	s_nop 0
	global_load_lds_dwordx4 v[140:141], off
	v_lshl_add_u64 v[140:141], s[48:49], 0, v[130:131]
	s_add_i32 m0, s47, 0x2000
	s_nop 0
	global_load_lds_dwordx4 v[140:141], off
	v_lshl_add_u64 v[140:141], v[212:213], 0, s[82:83]
	s_mov_b32 m0, s15
	s_nop 0
	global_load_lds_dwordx4 v[140:141], off
	v_lshl_add_u64 v[140:141], v[214:215], 0, s[82:83]
	s_mov_b32 m0, s33
	s_nop 0
	global_load_lds_dwordx4 v[140:141], off
	s_waitcnt vmcnt(8)
	s_waitcnt lgkmcnt(0)
	s_barrier
	s_setprio 1
	s_waitcnt lgkmcnt(0)
	v_mfma_f32_16x16x32_bf16 v[62:65], v[146:149], v[178:181], v[62:65]
	v_mfma_f32_16x16x32_bf16 v[58:61], v[154:157], v[178:181], v[58:61]
	v_mfma_f32_16x16x32_bf16 v[46:49], v[146:149], v[186:189], v[46:49]
	v_mfma_f32_16x16x32_bf16 v[42:45], v[154:157], v[186:189], v[42:45]
	v_mfma_f32_16x16x32_bf16 v[30:33], v[146:149], v[194:197], v[30:33]
	v_mfma_f32_16x16x32_bf16 v[26:29], v[154:157], v[194:197], v[26:29]
	v_mfma_f32_16x16x32_bf16 v[14:17], v[146:149], v[202:205], v[14:17]
	v_mfma_f32_16x16x32_bf16 v[10:13], v[154:157], v[202:205], v[10:13]
	v_mfma_f32_16x16x32_bf16 v[62:65], v[150:153], v[182:185], v[62:65]
	v_mfma_f32_16x16x32_bf16 v[58:61], v[158:161], v[182:185], v[58:61]
	v_mfma_f32_16x16x32_bf16 v[46:49], v[150:153], v[190:193], v[46:49]
	v_mfma_f32_16x16x32_bf16 v[42:45], v[158:161], v[190:193], v[42:45]
	v_mfma_f32_16x16x32_bf16 v[30:33], v[150:153], v[198:201], v[30:33]
	v_mfma_f32_16x16x32_bf16 v[26:29], v[158:161], v[198:201], v[26:29]
	v_mfma_f32_16x16x32_bf16 v[14:17], v[150:153], v[206:209], v[14:17]
	v_mfma_f32_16x16x32_bf16 v[10:13], v[158:161], v[206:209], v[10:13]
	s_setprio 0
	s_setprio 1
	v_mfma_f32_16x16x32_bf16 v[54:57], v[162:165], v[178:181], v[54:57]
	v_mfma_f32_16x16x32_bf16 v[50:53], v[170:173], v[178:181], v[50:53]
	v_mfma_f32_16x16x32_bf16 v[38:41], v[162:165], v[186:189], v[38:41]
	v_mfma_f32_16x16x32_bf16 v[34:37], v[170:173], v[186:189], v[34:37]
	v_mfma_f32_16x16x32_bf16 v[22:25], v[162:165], v[194:197], v[22:25]
	v_mfma_f32_16x16x32_bf16 v[18:21], v[170:173], v[194:197], v[18:21]
	v_mfma_f32_16x16x32_bf16 v[6:9], v[162:165], v[202:205], v[6:9]
	v_mfma_f32_16x16x32_bf16 v[2:5], v[170:173], v[202:205], v[2:5]
	v_mfma_f32_16x16x32_bf16 v[54:57], v[166:169], v[182:185], v[54:57]
	v_mfma_f32_16x16x32_bf16 v[50:53], v[174:177], v[182:185], v[50:53]
	v_mfma_f32_16x16x32_bf16 v[38:41], v[166:169], v[190:193], v[38:41]
	v_mfma_f32_16x16x32_bf16 v[34:37], v[174:177], v[190:193], v[34:37]
	v_mfma_f32_16x16x32_bf16 v[22:25], v[166:169], v[198:201], v[22:25]
	v_mfma_f32_16x16x32_bf16 v[18:21], v[174:177], v[198:201], v[18:21]
	v_mfma_f32_16x16x32_bf16 v[6:9], v[166:169], v[206:209], v[6:9]
	v_mfma_f32_16x16x32_bf16 v[2:5], v[174:177], v[206:209], v[2:5]
	s_setprio 0
	s_barrier
	s_add_i32 s46, s46, 2
	s_add_u32 s54, s54, 0x100
	s_addc_u32 s55, s55, 0
	s_add_u32 s43, s43, 0x100
	s_addc_u32 s45, s45, 0
	s_cmp_gt_u32 s46, 13
	s_cbranch_scc0 .LBB0_54
	s_and_b64 vcc, exec, s[28:29]
	s_cbranch_vccz .LBB0_57
	s_barrier

; #define PG8_STAGE(bufoff, gbase, voff) do { _Pragma("unroll") for (int _i = 0; _i < 2; ++_i) \
;         __builtin_amdgcn_global_load_lds((const unsigned*)((const char*)(gbase) + (voff)[_i]), (PG8_LAS unsigned*)(lds + (bufoff) + ldsw + _i * 8192), 16, 0, 0); } while (0)
; #define PG8_LDA(dst, b, h) do { _Pragma("unroll") for (int m = 0; m < 4; ++m) _Pragma("unroll") for (int k = 0; k < 2; ++k) dst[m][k] = *(const PG8_LAS bf16x8*)(lds + PG8_SA(b, h) + aoff + m * 2048 + k * 1024); } while (0)
; #define PG8_LDB(dst, b, h) do { _Pragma("unroll") for (int n = 0; n < 2; ++n) _Pragma("unroll") for (int k = 0; k < 2; ++k) dst[n][k] = *(const PG8_LAS bf16x8*)(lds + PG8_SB(b, h) + boff + n * 2048 + k * 1024); } while (0)
; #define PG8_MMA(ai, bj, At, Bt) do { __builtin_amdgcn_s_setprio(1); _Pragma("unroll") for (int m = 0; m < 4; ++m) _Pragma("unroll") for (int n = 0; n < 2; ++n) _Pragma("unroll") for (int k = 0; k < 2; ++k) \
;         acc[ai][bj][m][n] = __builtin_amdgcn_mfma_f32_16x16x32_bf16(Bt[n][k], At[m][k], acc[ai][bj][m][n], 0, 0, 0); __builtin_amdgcn_s_setprio(0); } while (0)
; #define PG8_WAIT_V(n) asm volatile("s_waitcnt vmcnt(" #n ")" ::: "memory")
; #define PG8_WAIT_L(n) asm volatile("s_waitcnt lgkmcnt(" #n ")" ::: "memory")
; #define PG8_BAR __builtin_amdgcn_s_barrier()
; template <class Epi, class Sched, bool ALIGN_EPI = false, bool SP2 = false, bool UNIFORM_NT = false>
; __device__ __forceinline__ void gemm_phase(PG8_LAS unsigned char* lds, const Gemm g, const Sched& S, const Epi& E, int tid_in) {
;     ...
;             const char* a1 = cA + (size_t)(t + 1) * kstep;
;             const char* a2 = last ? nA : cA + (size_t)(t + 2) * kstep; const char* b2 = last ? nB : cB + (size_t)(t + 2) * kstep;
;             const char* a3 = a2 + kstep; const char* b3 = b2 + kstep;
;             if (last && has_next) S.a_ready(nxt);
;             if constexpr (SP2) {
;             PG8_LDB(B0, 0, 0); PG8_LDB(B1, 0, 1); PG8_SCHED; PG8_LDA(At, 0, 0); PG8_STAGE(PG8_SA(1, 1), a1 + hstepA, voffA);
;             PG8_WAIT_V(8); PG8_WAIT_L(0); PG8_BAR; PG8_MMA(0, 0, At, B0); PG8_MMA(0, 1, At, B1); PG8_BAR; PG8_SCHED;
;             PG8_LDA(At, 0, 1); PG8_STAGE(PG8_SB(0, 0), b2, voffB); PG8_STAGE(PG8_SB(0, 1), b2 + hstepB, voffB); PG8_STAGE(PG8_SA(0, 0), a2, voffA);
;             PG8_WAIT_V(8); PG8_WAIT_L(0); PG8_BAR; PG8_MMA(1, 0, At, B0); PG8_MMA(1, 1, At, B1); PG8_BAR; PG8_SCHED;
.LBB0_112:
	s_add_i32 s43, 0, 0x10000
	v_add_u32_e32 v142, s43, v243
	ds_read_b128 v[130:133], v142
	ds_read_b128 v[134:137], v142 offset:1024
	ds_read_b128 v[138:141], v142 offset:2048
	ds_read_b128 v[142:145], v142 offset:3072
	s_add_i32 s37, s35, 2
	s_add_u32 s40, s10, 0x80
	s_addc_u32 s41, s11, 0
	s_cmp_eq_u32 s12, s35
	s_cselect_b32 s41, s85, s41
	s_cselect_b32 s40, s84, s40
	s_cselect_b32 s45, s69, s31
	s_cselect_b32 s44, s68, s13
	s_add_i32 s35, 0, 0x14000
	v_add_u32_e32 v158, s35, v243
	ds_read_b128 v[146:149], v158
	ds_read_b128 v[150:153], v158 offset:1024
	ds_read_b128 v[154:157], v158 offset:2048
	ds_read_b128 v[158:161], v158 offset:3072
	v_lshl_add_u64 v[204:205], s[10:11], 0, v[184:185]
	s_add_i32 m0, s64, 0xc000
	ds_read_b128 v[162:165], v244
	ds_read_b128 v[166:169], v244 offset:1024
	ds_read_b128 v[170:173], v244 offset:2048
	ds_read_b128 v[174:177], v244 offset:3072
	ds_read_b128 v[188:191], v244 offset:4096
	ds_read_b128 v[192:195], v244 offset:5120
	ds_read_b128 v[196:199], v244 offset:6144
	ds_read_b128 v[200:203], v244 offset:7168
	global_load_lds_dwordx4 v[204:205], off
	v_lshl_add_u64 v[204:205], s[10:11], 0, v[186:187]
	s_add_i32 m0, s64, 0xe000
	s_nop 0
	global_load_lds_dwordx4 v[204:205], off
	s_waitcnt vmcnt(8)
	s_waitcnt lgkmcnt(0)
	s_barrier
	s_setprio 1
	s_waitcnt lgkmcnt(0)
	v_mfma_f32_16x16x32_bf16 v[126:129], v[130:133], v[162:165], v[126:129]
	v_mfma_f32_16x16x32_bf16 v[122:125], v[138:141], v[162:165], v[122:125]
	v_mfma_f32_16x16x32_bf16 v[118:121], v[130:133], v[170:173], v[118:121]
	v_mfma_f32_16x16x32_bf16 v[114:117], v[138:141], v[170:173], v[114:117]
	v_mfma_f32_16x16x32_bf16 v[110:113], v[130:133], v[188:191], v[110:113]
	v_mfma_f32_16x16x32_bf16 v[106:109], v[138:141], v[188:191], v[106:109]
	v_mfma_f32_16x16x32_bf16 v[102:105], v[130:133], v[196:199], v[102:105]
	v_mfma_f32_16x16x32_bf16 v[98:101], v[138:141], v[196:199], v[98:101]
	v_mfma_f32_16x16x32_bf16 v[126:129], v[134:137], v[166:169], v[126:129]
	v_mfma_f32_16x16x32_bf16 v[122:125], v[142:145], v[166:169], v[122:125]
	v_mfma_f32_16x16x32_bf16 v[118:121], v[134:137], v[174:177], v[118:121]
	v_mfma_f32_16x16x32_bf16 v[114:117], v[142:145], v[174:177], v[114:117]
	v_mfma_f32_16x16x32_bf16 v[110:113], v[134:137], v[192:195], v[110:113]
	v_mfma_f32_16x16x32_bf16 v[106:109], v[142:145], v[192:195], v[106:109]
	v_mfma_f32_16x16x32_bf16 v[102:105], v[134:137], v[200:203], v[102:105]
	v_mfma_f32_16x16x32_bf16 v[98:101], v[142:145], v[200:203], v[98:101]
	s_setprio 0
	s_setprio 1
	v_mfma_f32_16x16x32_bf16 v[62:65], v[146:149], v[162:165], v[62:65]
	v_mfma_f32_16x16x32_bf16 v[58:61], v[154:157], v[162:165], v[58:61]
	v_mfma_f32_16x16x32_bf16 v[54:57], v[146:149], v[170:173], v[54:57]
	v_mfma_f32_16x16x32_bf16 v[50:53], v[154:157], v[170:173], v[50:53]
	v_mfma_f32_16x16x32_bf16 v[46:49], v[146:149], v[188:191], v[46:49]
	v_mfma_f32_16x16x32_bf16 v[42:45], v[154:157], v[188:191], v[42:45]
	v_mfma_f32_16x16x32_bf16 v[38:41], v[146:149], v[196:199], v[38:41]
	v_mfma_f32_16x16x32_bf16 v[34:37], v[154:157], v[196:199], v[34:37]
	v_mfma_f32_16x16x32_bf16 v[62:65], v[150:153], v[166:169], v[62:65]
	v_mfma_f32_16x16x32_bf16 v[58:61], v[158:161], v[166:169], v[58:61]
	v_mfma_f32_16x16x32_bf16 v[54:57], v[150:153], v[174:177], v[54:57]
	v_mfma_f32_16x16x32_bf16 v[50:53], v[158:161], v[174:177], v[50:53]
	v_mfma_f32_16x16x32_bf16 v[46:49], v[150:153], v[192:195], v[46:49]
	v_mfma_f32_16x16x32_bf16 v[42:45], v[158:161], v[192:195], v[42:45]
	v_mfma_f32_16x16x32_bf16 v[38:41], v[150:153], v[200:203], v[38:41]
	v_mfma_f32_16x16x32_bf16 v[34:37], v[158:161], v[200:203], v[34:37]
	s_setprio 0
	s_barrier
	s_add_i32 s43, s43, s49
	v_lshl_add_u64 v[204:205], s[44:45], 0, v[0:1]
	s_mov_b32 m0, s43
	ds_read_b128 v[162:165], v244 offset:16384
	ds_read_b128 v[166:169], v244 offset:17408
	ds_read_b128 v[170:173], v244 offset:18432
	ds_read_b128 v[174:177], v244 offset:19456
	ds_read_b128 v[188:191], v244 offset:20480
	ds_read_b128 v[192:195], v244 offset:21504
	ds_read_b128 v[196:199], v244 offset:22528
	ds_read_b128 v[200:203], v244 offset:23552
	global_load_lds_dwordx4 v[204:205], off
	s_add_i32 m0, s43, 0x2000
	v_lshl_add_u64 v[206:207], s[44:45], 0, v[182:183]
	s_add_u32 s44, s44, s26
	s_addc_u32 s45, s45, 0
	s_add_i32 s35, s35, s49
	global_load_lds_dwordx4 v[206:207], off
	v_lshl_add_u64 v[208:209], s[44:45], 0, v[0:1]
	s_mov_b32 m0, s35
	v_lshl_add_u64 v[210:211], s[44:45], 0, v[182:183]
	global_load_lds_dwordx4 v[208:209], off
	s_add_i32 m0, s35, 0x2000
	v_lshl_add_u64 v[212:213], s[40:41], 0, v[178:179]
	global_load_lds_dwordx4 v[210:211], off
	s_mov_b32 m0, s64
	v_lshl_add_u64 v[214:215], s[40:41], 0, v[180:181]
	global_load_lds_dwordx4 v[212:213], off
	s_mov_b32 m0, s78
	s_nop 0
	global_load_lds_dwordx4 v[214:215], off
	s_waitcnt vmcnt(8)
	s_waitcnt lgkmcnt(0)
	s_barrier
; #define PG8_STAGE(bufoff, gbase, voff) do { _Pragma("unroll") for (int _i = 0; _i < 2; ++_i) \
;         __builtin_amdgcn_global_load_lds((const unsigned*)((const char*)(gbase) + (voff)[_i]), (PG8_LAS unsigned*)(lds + (bufoff) + ldsw + _i * 8192), 16, 0, 0); } while (0)
; #define PG8_LDA(dst, b, h) do { _Pragma("unroll") for (int m = 0; m < 4; ++m) _Pragma("unroll") for (int k = 0; k < 2; ++k) dst[m][k] = *(const PG8_LAS bf16x8*)(lds + PG8_SA(b, h) + aoff + m * 2048 + k * 1024); } while (0)
; #define PG8_LDB(dst, b, h) do { _Pragma("unroll") for (int n = 0; n < 2; ++n) _Pragma("unroll") for (int k = 0; k < 2; ++k) dst[n][k] = *(const PG8_LAS bf16x8*)(lds + PG8_SB(b, h) + boff + n * 2048 + k * 1024); } while (0)
; #define PG8_MMA(ai, bj, At, Bt) do { __builtin_amdgcn_s_setprio(1); _Pragma("unroll") for (int m = 0; m < 4; ++m) _Pragma("unroll") for (int n = 0; n < 2; ++n) _Pragma("unroll") for (int k = 0; k < 2; ++k) \
;         acc[ai][bj][m][n] = __builtin_amdgcn_mfma_f32_16x16x32_bf16(Bt[n][k], At[m][k], acc[ai][bj][m][n], 0, 0, 0); __builtin_amdgcn_s_setprio(0); } while (0)
; #define PG8_WAIT_V(n) asm volatile("s_waitcnt vmcnt(" #n ")" ::: "memory")
; #define PG8_WAIT_L(n) asm volatile("s_waitcnt lgkmcnt(" #n ")" ::: "memory")
; #define PG8_BAR __builtin_amdgcn_s_barrier()
; #define PG8_SCHED __builtin_amdgcn_sched_barrier(0)
; template <class Epi, class Sched, bool ALIGN_EPI = false, bool SP2 = false, bool UNIFORM_NT = false>
; __device__ __forceinline__ void gemm_phase(PG8_LAS unsigned char* lds, const Gemm g, const Sched& S, const Epi& E, int tid_in) {
;     ...
;             PG8_WAIT_V(8); PG8_WAIT_L(0); PG8_BAR; PG8_MMA(1, 0, At, B0); PG8_MMA(1, 1, At, B1); PG8_BAR; PG8_SCHED;
;             PG8_LDB(B0, 1, 0); PG8_LDB(B1, 1, 1); PG8_SCHED; PG8_LDA(At, 1, 0); PG8_STAGE(PG8_SA(0, 1), a2 + hstepA, voffA);
;             PG8_WAIT_V(8); PG8_WAIT_L(0); PG8_BAR; PG8_MMA(0, 0, At, B0); PG8_MMA(0, 1, At, B1); PG8_BAR; PG8_SCHED;
	s_setprio 1
	s_waitcnt lgkmcnt(0)
	v_mfma_f32_16x16x32_bf16 v[94:97], v[130:133], v[162:165], v[94:97]
	v_mfma_f32_16x16x32_bf16 v[90:93], v[138:141], v[162:165], v[90:93]
	v_mfma_f32_16x16x32_bf16 v[86:89], v[130:133], v[170:173], v[86:89]
	v_mfma_f32_16x16x32_bf16 v[82:85], v[138:141], v[170:173], v[82:85]
	v_mfma_f32_16x16x32_bf16 v[78:81], v[130:133], v[188:191], v[78:81]
	v_mfma_f32_16x16x32_bf16 v[74:77], v[138:141], v[188:191], v[74:77]
	v_mfma_f32_16x16x32_bf16 v[70:73], v[130:133], v[196:199], v[70:73]
	v_mfma_f32_16x16x32_bf16 v[66:69], v[138:141], v[196:199], v[66:69]
	v_mfma_f32_16x16x32_bf16 v[94:97], v[134:137], v[166:169], v[94:97]
	v_mfma_f32_16x16x32_bf16 v[90:93], v[142:145], v[166:169], v[90:93]
	v_mfma_f32_16x16x32_bf16 v[86:89], v[134:137], v[174:177], v[86:89]
	v_mfma_f32_16x16x32_bf16 v[82:85], v[142:145], v[174:177], v[82:85]
	v_mfma_f32_16x16x32_bf16 v[78:81], v[134:137], v[192:195], v[78:81]
	v_mfma_f32_16x16x32_bf16 v[74:77], v[142:145], v[192:195], v[74:77]
	v_mfma_f32_16x16x32_bf16 v[70:73], v[134:137], v[200:203], v[70:73]
	v_mfma_f32_16x16x32_bf16 v[66:69], v[142:145], v[200:203], v[66:69]
	s_setprio 0
	s_setprio 1
	v_mfma_f32_16x16x32_bf16 v[30:33], v[146:149], v[162:165], v[30:33]
	v_mfma_f32_16x16x32_bf16 v[26:29], v[154:157], v[162:165], v[26:29]
	v_mfma_f32_16x16x32_bf16 v[22:25], v[146:149], v[170:173], v[22:25]
	v_mfma_f32_16x16x32_bf16 v[18:21], v[154:157], v[170:173], v[18:21]
	v_mfma_f32_16x16x32_bf16 v[14:17], v[146:149], v[188:191], v[14:17]
	v_mfma_f32_16x16x32_bf16 v[10:13], v[154:157], v[188:191], v[10:13]
	v_mfma_f32_16x16x32_bf16 v[6:9], v[146:149], v[196:199], v[6:9]
	v_mfma_f32_16x16x32_bf16 v[2:5], v[154:157], v[196:199], v[2:5]
	v_mfma_f32_16x16x32_bf16 v[30:33], v[150:153], v[166:169], v[30:33]
	v_mfma_f32_16x16x32_bf16 v[26:29], v[158:161], v[166:169], v[26:29]
	v_mfma_f32_16x16x32_bf16 v[22:25], v[150:153], v[174:177], v[22:25]
	v_mfma_f32_16x16x32_bf16 v[18:21], v[158:161], v[174:177], v[18:21]
	v_mfma_f32_16x16x32_bf16 v[14:17], v[150:153], v[192:195], v[14:17]
	v_mfma_f32_16x16x32_bf16 v[10:13], v[158:161], v[192:195], v[10:13]
	v_mfma_f32_16x16x32_bf16 v[6:9], v[150:153], v[200:203], v[6:9]
	v_mfma_f32_16x16x32_bf16 v[2:5], v[158:161], v[200:203], v[2:5]
	s_setprio 0
	s_barrier
	s_add_i32 s35, 0, 0x18000
	s_add_i32 s43, 0, 0x1c000
	v_add_u32_e32 v142, s35, v243
	v_add_u32_e32 v158, s43, v243
	ds_read_b128 v[130:133], v142
	ds_read_b128 v[134:137], v142 offset:1024
	ds_read_b128 v[138:141], v142 offset:2048
	ds_read_b128 v[142:145], v142 offset:3072
	ds_read_b128 v[146:149], v158
	ds_read_b128 v[150:153], v158 offset:1024
	ds_read_b128 v[154:157], v158 offset:2048
	ds_read_b128 v[158:161], v158 offset:3072
	s_add_u32 s40, s40, s26
	s_addc_u32 s41, s41, 0
	s_mov_b32 m0, s79
	v_lshl_add_u64 v[216:217], s[40:41], 0, v[178:179]
	ds_read_b128 v[162:165], v244 offset:32768
	ds_read_b128 v[166:169], v244 offset:33792
	ds_read_b128 v[170:173], v244 offset:34816
	ds_read_b128 v[174:177], v244 offset:35840
	ds_read_b128 v[188:191], v244 offset:36864
	ds_read_b128 v[192:195], v244 offset:37888
	ds_read_b128 v[196:199], v244 offset:38912
	ds_read_b128 v[200:203], v244 offset:39936
	global_load_lds_dwordx4 v[216:217], off
	v_lshl_add_u64 v[216:217], s[40:41], 0, v[180:181]
	s_mov_b32 m0, s88
	s_nop 0
	global_load_lds_dwordx4 v[216:217], off
	s_waitcnt vmcnt(8)
	s_waitcnt lgkmcnt(0)
	s_barrier
	s_setprio 1
	s_waitcnt lgkmcnt(0)
	v_mfma_f32_16x16x32_bf16 v[126:129], v[130:133], v[162:165], v[126:129]
	v_mfma_f32_16x16x32_bf16 v[122:125], v[138:141], v[162:165], v[122:125]
	v_mfma_f32_16x16x32_bf16 v[118:121], v[130:133], v[170:173], v[118:121]
	v_mfma_f32_16x16x32_bf16 v[114:117], v[138:141], v[170:173], v[114:117]
	v_mfma_f32_16x16x32_bf16 v[110:113], v[130:133], v[188:191], v[110:113]
	v_mfma_f32_16x16x32_bf16 v[106:109], v[138:141], v[188:191], v[106:109]
	v_mfma_f32_16x16x32_bf16 v[102:105], v[130:133], v[196:199], v[102:105]
	v_mfma_f32_16x16x32_bf16 v[98:101], v[138:141], v[196:199], v[98:101]
	v_mfma_f32_16x16x32_bf16 v[126:129], v[134:137], v[166:169], v[126:129]
	v_mfma_f32_16x16x32_bf16 v[122:125], v[142:145], v[166:169], v[122:125]
	v_mfma_f32_16x16x32_bf16 v[118:121], v[134:137], v[174:177], v[118:121]
	v_mfma_f32_16x16x32_bf16 v[114:117], v[142:145], v[174:177], v[114:117]
	v_mfma_f32_16x16x32_bf16 v[110:113], v[134:137], v[192:195], v[110:113]
	v_mfma_f32_16x16x32_bf16 v[106:109], v[142:145], v[192:195], v[106:109]
	v_mfma_f32_16x16x32_bf16 v[102:105], v[134:137], v[200:203], v[102:105]
	v_mfma_f32_16x16x32_bf16 v[98:101], v[142:145], v[200:203], v[98:101]
	s_setprio 0
	s_setprio 1
	v_mfma_f32_16x16x32_bf16 v[62:65], v[146:149], v[162:165], v[62:65]
	v_mfma_f32_16x16x32_bf16 v[58:61], v[154:157], v[162:165], v[58:61]
	v_mfma_f32_16x16x32_bf16 v[54:57], v[146:149], v[170:173], v[54:57]
	v_mfma_f32_16x16x32_bf16 v[50:53], v[154:157], v[170:173], v[50:53]
	v_mfma_f32_16x16x32_bf16 v[46:49], v[146:149], v[188:191], v[46:49]
	v_mfma_f32_16x16x32_bf16 v[42:45], v[154:157], v[188:191], v[42:45]
	v_mfma_f32_16x16x32_bf16 v[38:41], v[146:149], v[196:199], v[38:41]
	v_mfma_f32_16x16x32_bf16 v[34:37], v[154:157], v[196:199], v[34:37]
	v_mfma_f32_16x16x32_bf16 v[62:65], v[150:153], v[166:169], v[62:65]
	v_mfma_f32_16x16x32_bf16 v[58:61], v[158:161], v[166:169], v[58:61]
	v_mfma_f32_16x16x32_bf16 v[54:57], v[150:153], v[174:177], v[54:57]
	v_mfma_f32_16x16x32_bf16 v[50:53], v[158:161], v[174:177], v[50:53]
	v_mfma_f32_16x16x32_bf16 v[46:49], v[150:153], v[192:195], v[46:49]
	v_mfma_f32_16x16x32_bf16 v[42:45], v[158:161], v[192:195], v[42:45]
	v_mfma_f32_16x16x32_bf16 v[38:41], v[150:153], v[200:203], v[38:41]
	v_mfma_f32_16x16x32_bf16 v[34:37], v[158:161], v[200:203], v[34:37]
	s_setprio 0
	s_barrier
; #define PG8_STAGE(bufoff, gbase, voff) do { _Pragma("unroll") for (int _i = 0; _i < 2; ++_i) \
;         __builtin_amdgcn_global_load_lds((const unsigned*)((const char*)(gbase) + (voff)[_i]), (PG8_LAS unsigned*)(lds + (bufoff) + ldsw + _i * 8192), 16, 0, 0); } while (0)
; #define PG8_LDA(dst, b, h) do { _Pragma("unroll") for (int m = 0; m < 4; ++m) _Pragma("unroll") for (int k = 0; k < 2; ++k) dst[m][k] = *(const PG8_LAS bf16x8*)(lds + PG8_SA(b, h) + aoff + m * 2048 + k * 1024); } while (0)
; #define PG8_MMA(ai, bj, At, Bt) do { __builtin_amdgcn_s_setprio(1); _Pragma("unroll") for (int m = 0; m < 4; ++m) _Pragma("unroll") for (int n = 0; n < 2; ++n) _Pragma("unroll") for (int k = 0; k < 2; ++k) \
;         acc[ai][bj][m][n] = __builtin_amdgcn_mfma_f32_16x16x32_bf16(Bt[n][k], At[m][k], acc[ai][bj][m][n], 0, 0, 0); __builtin_amdgcn_s_setprio(0); } while (0)
; #define PG8_WAIT_V(n) asm volatile("s_waitcnt vmcnt(" #n ")" ::: "memory")
; #define PG8_WAIT_L(n) asm volatile("s_waitcnt lgkmcnt(" #n ")" ::: "memory")
; #define PG8_BAR __builtin_amdgcn_s_barrier()
; #define PG8_SCHED __builtin_amdgcn_sched_barrier(0)
; template <class Epi, class Sched, bool ALIGN_EPI = false, bool SP2 = false, bool UNIFORM_NT = false>
; __device__ __forceinline__ void gemm_phase(PG8_LAS unsigned char* lds, const Gemm g, const Sched& S, const Epi& E, int tid_in) {
;     ...
;             PG8_LDA(At, 1, 1); PG8_STAGE(PG8_SB(1, 0), b3, voffB); PG8_STAGE(PG8_SB(1, 1), b3 + hstepB, voffB); PG8_STAGE(PG8_SA(1, 0), a3, voffA);
;             PG8_WAIT_V(8); PG8_WAIT_L(0); PG8_BAR; PG8_MMA(1, 0, At, B0); PG8_MMA(1, 1, At, B1); PG8_BAR; PG8_SCHED;
	s_add_i32 s35, s35, s49
	v_lshl_add_u64 v[204:205], v[204:205], 0, s[82:83]
	s_mov_b32 m0, s35
	ds_read_b128 v[162:165], v244 offset:49152
	ds_read_b128 v[166:169], v244 offset:50176
	ds_read_b128 v[170:173], v244 offset:51200
	ds_read_b128 v[174:177], v244 offset:52224
	ds_read_b128 v[188:191], v244 offset:53248
	ds_read_b128 v[192:195], v244 offset:54272
	ds_read_b128 v[196:199], v244 offset:55296
	ds_read_b128 v[200:203], v244 offset:56320
	global_load_lds_dwordx4 v[204:205], off
	v_lshl_add_u64 v[204:205], v[206:207], 0, s[82:83]
	s_add_i32 m0, s35, 0x2000
	s_add_i32 s35, s43, s49
	global_load_lds_dwordx4 v[204:205], off
	v_lshl_add_u64 v[204:205], v[208:209], 0, s[82:83]
	s_mov_b32 m0, s35
	s_nop 0
	global_load_lds_dwordx4 v[204:205], off
	v_lshl_add_u64 v[204:205], v[210:211], 0, s[82:83]
	s_add_i32 m0, s35, 0x2000
	s_nop 0
	global_load_lds_dwordx4 v[204:205], off
	v_lshl_add_u64 v[204:205], v[212:213], 0, s[82:83]
	s_mov_b32 m0, s94
	s_nop 0
	global_load_lds_dwordx4 v[204:205], off
	v_lshl_add_u64 v[204:205], v[214:215], 0, s[82:83]
	s_mov_b32 m0, s89
	s_nop 0
	global_load_lds_dwordx4 v[204:205], off
	s_waitcnt vmcnt(8)
	s_waitcnt lgkmcnt(0)
	s_barrier
	s_setprio 1
	s_waitcnt lgkmcnt(0)
	v_mfma_f32_16x16x32_bf16 v[94:97], v[130:133], v[162:165], v[94:97]
	v_mfma_f32_16x16x32_bf16 v[90:93], v[138:141], v[162:165], v[90:93]
	v_mfma_f32_16x16x32_bf16 v[86:89], v[130:133], v[170:173], v[86:89]
	v_mfma_f32_16x16x32_bf16 v[82:85], v[138:141], v[170:173], v[82:85]
	v_mfma_f32_16x16x32_bf16 v[78:81], v[130:133], v[188:191], v[78:81]
	v_mfma_f32_16x16x32_bf16 v[74:77], v[138:141], v[188:191], v[74:77]
	v_mfma_f32_16x16x32_bf16 v[70:73], v[130:133], v[196:199], v[70:73]
	v_mfma_f32_16x16x32_bf16 v[66:69], v[138:141], v[196:199], v[66:69]
	v_mfma_f32_16x16x32_bf16 v[94:97], v[134:137], v[166:169], v[94:97]
	v_mfma_f32_16x16x32_bf16 v[90:93], v[142:145], v[166:169], v[90:93]
	v_mfma_f32_16x16x32_bf16 v[86:89], v[134:137], v[174:177], v[86:89]
	v_mfma_f32_16x16x32_bf16 v[82:85], v[142:145], v[174:177], v[82:85]
	v_mfma_f32_16x16x32_bf16 v[78:81], v[134:137], v[192:195], v[78:81]
	v_mfma_f32_16x16x32_bf16 v[74:77], v[142:145], v[192:195], v[74:77]
	v_mfma_f32_16x16x32_bf16 v[70:73], v[134:137], v[200:203], v[70:73]
	v_mfma_f32_16x16x32_bf16 v[66:69], v[142:145], v[200:203], v[66:69]
	s_setprio 0
	s_setprio 1
	v_mfma_f32_16x16x32_bf16 v[30:33], v[146:149], v[162:165], v[30:33]
	v_mfma_f32_16x16x32_bf16 v[26:29], v[154:157], v[162:165], v[26:29]
	v_mfma_f32_16x16x32_bf16 v[22:25], v[146:149], v[170:173], v[22:25]
	v_mfma_f32_16x16x32_bf16 v[18:21], v[154:157], v[170:173], v[18:21]
	v_mfma_f32_16x16x32_bf16 v[14:17], v[146:149], v[188:191], v[14:17]
	v_mfma_f32_16x16x32_bf16 v[10:13], v[154:157], v[188:191], v[10:13]
	v_mfma_f32_16x16x32_bf16 v[6:9], v[146:149], v[196:199], v[6:9]
	v_mfma_f32_16x16x32_bf16 v[2:5], v[154:157], v[196:199], v[2:5]
	v_mfma_f32_16x16x32_bf16 v[30:33], v[150:153], v[166:169], v[30:33]
	v_mfma_f32_16x16x32_bf16 v[26:29], v[158:161], v[166:169], v[26:29]
	v_mfma_f32_16x16x32_bf16 v[22:25], v[150:153], v[174:177], v[22:25]
	v_mfma_f32_16x16x32_bf16 v[18:21], v[158:161], v[174:177], v[18:21]
	v_mfma_f32_16x16x32_bf16 v[14:17], v[150:153], v[192:195], v[14:17]
	v_mfma_f32_16x16x32_bf16 v[10:13], v[158:161], v[192:195], v[10:13]
	v_mfma_f32_16x16x32_bf16 v[6:9], v[150:153], v[200:203], v[6:9]
	v_mfma_f32_16x16x32_bf16 v[2:5], v[158:161], v[200:203], v[2:5]
	s_setprio 0
	s_barrier
	s_add_u32 s10, s10, 0x100
	s_addc_u32 s11, s11, 0
	s_add_u32 s13, s13, 0x100
	s_addc_u32 s31, s31, 0
	s_cmp_ge_i32 s37, s15
	s_mov_b32 s35, s37
	s_cbranch_scc0 .LBB0_112
	s_and_b64 vcc, exec, s[62:63]
	s_cbranch_vccz .LBB0_115
	s_barrier

; #define PG8_STAGE(bufoff, gbase, voff) do { _Pragma("unroll") for (int _i = 0; _i < 2; ++_i) \
;         __builtin_amdgcn_global_load_lds((const unsigned*)((const char*)(gbase) + (voff)[_i]), (PG8_LAS unsigned*)(lds + (bufoff) + ldsw + _i * 8192), 16, 0, 0); } while (0)
; #define PG8_LDA(dst, b, h) do { _Pragma("unroll") for (int m = 0; m < 4; ++m) _Pragma("unroll") for (int k = 0; k < 2; ++k) dst[m][k] = *(const PG8_LAS bf16x8*)(lds + PG8_SA(b, h) + aoff + m * 2048 + k * 1024); } while (0)
; #define PG8_LDB(dst, b, h) do { _Pragma("unroll") for (int n = 0; n < 2; ++n) _Pragma("unroll") for (int k = 0; k < 2; ++k) dst[n][k] = *(const PG8_LAS bf16x8*)(lds + PG8_SB(b, h) + boff + n * 2048 + k * 1024); } while (0)
; #define PG8_MMA(ai, bj, At, Bt) do { __builtin_amdgcn_s_setprio(1); _Pragma("unroll") for (int m = 0; m < 4; ++m) _Pragma("unroll") for (int n = 0; n < 2; ++n) _Pragma("unroll") for (int k = 0; k < 2; ++k) \
;         acc[ai][bj][m][n] = __builtin_amdgcn_mfma_f32_16x16x32_bf16(Bt[n][k], At[m][k], acc[ai][bj][m][n], 0, 0, 0); __builtin_amdgcn_s_setprio(0); } while (0)
; #define PG8_WAIT_V(n) asm volatile("s_waitcnt vmcnt(" #n ")" ::: "memory")
; #define PG8_WAIT_L(n) asm volatile("s_waitcnt lgkmcnt(" #n ")" ::: "memory")
; #define PG8_BAR __builtin_amdgcn_s_barrier()
; template <class Epi, class Sched, bool ALIGN_EPI = false, bool SP2 = false, bool UNIFORM_NT = false>
; __device__ __forceinline__ void gemm_phase(PG8_LAS unsigned char* lds, const Gemm g, const Sched& S, const Epi& E, int tid_in) {
;     ...
;             const char* a1 = cA + (size_t)(t + 1) * kstep;
;             const char* a2 = last ? nA : cA + (size_t)(t + 2) * kstep; const char* b2 = last ? nB : cB + (size_t)(t + 2) * kstep;
;             const char* a3 = a2 + kstep; const char* b3 = b2 + kstep;
;             if (last && has_next) S.a_ready(nxt);
;             if constexpr (SP2) {
;             PG8_LDB(B0, 0, 0); PG8_LDB(B1, 0, 1); PG8_SCHED; PG8_LDA(At, 0, 0); PG8_STAGE(PG8_SA(1, 1), a1 + hstepA, voffA);
;             PG8_WAIT_V(8); PG8_WAIT_L(0); PG8_BAR; PG8_MMA(0, 0, At, B0); PG8_MMA(0, 1, At, B1); PG8_BAR; PG8_SCHED;
;             PG8_LDA(At, 0, 1); PG8_STAGE(PG8_SB(0, 0), b2, voffB); PG8_STAGE(PG8_SB(0, 1), b2 + hstepB, voffB); PG8_STAGE(PG8_SA(0, 0), a2, voffA);
;             PG8_WAIT_V(8); PG8_WAIT_L(0); PG8_BAR; PG8_MMA(1, 0, At, B0); PG8_MMA(1, 1, At, B1); PG8_BAR; PG8_SCHED;
.LBB0_833:
	s_add_i32 s40, 0, 0x10000
	v_add_u32_e32 v156, s40, v145
	ds_read_b128 v[140:143], v156
	ds_read_b128 v[148:151], v156 offset:1024
	ds_read_b128 v[152:155], v156 offset:2048
	ds_read_b128 v[156:159], v156 offset:3072
	s_add_u32 s26, s24, 0xfffc0080
	s_addc_u32 s27, s25, -1
	s_cmp_eq_u32 s37, 12
	s_cselect_b32 s29, s11, s27
	s_cselect_b32 s28, s12, s26
	s_cselect_b32 s27, s13, s36
	s_cselect_b32 s26, s19, s35
	s_add_i32 s42, 0, 0x14000
	v_add_u32_e32 v164, s42, v145
	ds_read_b128 v[160:163], v164
	ds_read_b128 v[178:181], v164 offset:1024
	ds_read_b128 v[182:185], v164 offset:2048
	ds_read_b128 v[186:189], v164 offset:3072
	v_lshl_add_u64 v[164:165], s[24:25], 0, v[136:137]
	s_add_i32 m0, s8, 0xc000
	ds_read_b128 v[190:193], v147
	ds_read_b128 v[194:197], v147 offset:1024
	ds_read_b128 v[198:201], v147 offset:2048
	ds_read_b128 v[202:205], v147 offset:3072
	ds_read_b128 v[206:209], v147 offset:4096
	ds_read_b128 v[210:213], v147 offset:5120
	ds_read_b128 v[214:217], v147 offset:6144
	ds_read_b128 v[218:221], v147 offset:7168
	global_load_lds_dwordx4 v[164:165], off
	v_lshl_add_u64 v[164:165], s[24:25], 0, v[138:139]
	s_add_i32 m0, s8, 0xe000
	s_nop 0
	global_load_lds_dwordx4 v[164:165], off
	s_waitcnt vmcnt(8)
	s_waitcnt lgkmcnt(0)
	s_barrier
	s_setprio 1
	s_waitcnt lgkmcnt(0)
	v_mfma_f32_16x16x32_bf16 v[126:129], v[140:143], v[190:193], v[126:129]
	v_mfma_f32_16x16x32_bf16 v[122:125], v[152:155], v[190:193], v[122:125]
	v_mfma_f32_16x16x32_bf16 v[118:121], v[140:143], v[198:201], v[118:121]
	v_mfma_f32_16x16x32_bf16 v[110:113], v[152:155], v[198:201], v[110:113]
	v_mfma_f32_16x16x32_bf16 v[102:105], v[140:143], v[206:209], v[102:105]
	v_mfma_f32_16x16x32_bf16 v[94:97], v[152:155], v[206:209], v[94:97]
	v_mfma_f32_16x16x32_bf16 v[86:89], v[140:143], v[214:217], v[86:89]
	v_mfma_f32_16x16x32_bf16 v[78:81], v[152:155], v[214:217], v[78:81]
	v_mfma_f32_16x16x32_bf16 v[126:129], v[148:151], v[194:197], v[126:129]
	v_mfma_f32_16x16x32_bf16 v[122:125], v[156:159], v[194:197], v[122:125]
	v_mfma_f32_16x16x32_bf16 v[118:121], v[148:151], v[202:205], v[118:121]
	v_mfma_f32_16x16x32_bf16 v[110:113], v[156:159], v[202:205], v[110:113]
	v_mfma_f32_16x16x32_bf16 v[102:105], v[148:151], v[210:213], v[102:105]
	v_mfma_f32_16x16x32_bf16 v[94:97], v[156:159], v[210:213], v[94:97]
	v_mfma_f32_16x16x32_bf16 v[86:89], v[148:151], v[218:221], v[86:89]
	v_mfma_f32_16x16x32_bf16 v[78:81], v[156:159], v[218:221], v[78:81]
	s_setprio 0
	s_setprio 1
	v_mfma_f32_16x16x32_bf16 v[114:117], v[160:163], v[190:193], v[114:117]
	v_mfma_f32_16x16x32_bf16 v[106:109], v[182:185], v[190:193], v[106:109]
	v_mfma_f32_16x16x32_bf16 v[98:101], v[160:163], v[198:201], v[98:101]
	v_mfma_f32_16x16x32_bf16 v[90:93], v[182:185], v[198:201], v[90:93]
	v_mfma_f32_16x16x32_bf16 v[82:85], v[160:163], v[206:209], v[82:85]
	v_mfma_f32_16x16x32_bf16 v[74:77], v[182:185], v[206:209], v[74:77]
	v_mfma_f32_16x16x32_bf16 v[70:73], v[160:163], v[214:217], v[70:73]
	v_mfma_f32_16x16x32_bf16 v[66:69], v[182:185], v[214:217], v[66:69]
	v_mfma_f32_16x16x32_bf16 v[114:117], v[178:181], v[194:197], v[114:117]
	v_mfma_f32_16x16x32_bf16 v[106:109], v[186:189], v[194:197], v[106:109]
	v_mfma_f32_16x16x32_bf16 v[98:101], v[178:181], v[202:205], v[98:101]
	v_mfma_f32_16x16x32_bf16 v[90:93], v[186:189], v[202:205], v[90:93]
	v_mfma_f32_16x16x32_bf16 v[82:85], v[178:181], v[210:213], v[82:85]
	v_mfma_f32_16x16x32_bf16 v[74:77], v[186:189], v[210:213], v[74:77]
	v_mfma_f32_16x16x32_bf16 v[70:73], v[178:181], v[218:221], v[70:73]
	v_mfma_f32_16x16x32_bf16 v[66:69], v[186:189], v[218:221], v[66:69]
	s_setprio 0
	s_barrier
	s_add_i32 s40, s40, s3
	v_lshl_add_u64 v[164:165], s[26:27], 0, v[0:1]
	s_mov_b32 m0, s40
	ds_read_b128 v[190:193], v147 offset:16384
	ds_read_b128 v[194:197], v147 offset:17408
	ds_read_b128 v[198:201], v147 offset:18432
	ds_read_b128 v[202:205], v147 offset:19456
	ds_read_b128 v[206:209], v147 offset:20480
	ds_read_b128 v[210:213], v147 offset:21504
	ds_read_b128 v[214:217], v147 offset:22528
	ds_read_b128 v[218:221], v147 offset:23552
	global_load_lds_dwordx4 v[164:165], off
	s_add_i32 m0, s40, 0x2000
	s_add_u32 s40, s26, 0x40000
	v_lshl_add_u64 v[166:167], s[26:27], 0, v[130:131]
	s_addc_u32 s41, s27, 0
	s_add_i32 s42, s42, s3
	global_load_lds_dwordx4 v[166:167], off
	v_lshl_add_u64 v[168:169], s[40:41], 0, v[0:1]
	s_mov_b32 m0, s42
	v_lshl_add_u64 v[170:171], s[28:29], 0, v[132:133]
	global_load_lds_dwordx4 v[168:169], off
	v_lshl_add_u64 v[168:169], s[40:41], 0, v[130:131]
	s_add_i32 m0, s42, 0x2000
	s_nop 0
	global_load_lds_dwordx4 v[168:169], off
	v_lshl_add_u64 v[168:169], s[28:29], 0, v[134:135]
	s_mov_b32 m0, s8
	s_nop 0
	global_load_lds_dwordx4 v[168:169], off
	s_mov_b32 m0, s9
	s_nop 0
	global_load_lds_dwordx4 v[170:171], off
	s_waitcnt vmcnt(8)
	s_waitcnt lgkmcnt(0)
	s_barrier
; #define PG8_STAGE(bufoff, gbase, voff) do { _Pragma("unroll") for (int _i = 0; _i < 2; ++_i) \
;         __builtin_amdgcn_global_load_lds((const unsigned*)((const char*)(gbase) + (voff)[_i]), (PG8_LAS unsigned*)(lds + (bufoff) + ldsw + _i * 8192), 16, 0, 0); } while (0)
; #define PG8_LDA(dst, b, h) do { _Pragma("unroll") for (int m = 0; m < 4; ++m) _Pragma("unroll") for (int k = 0; k < 2; ++k) dst[m][k] = *(const PG8_LAS bf16x8*)(lds + PG8_SA(b, h) + aoff + m * 2048 + k * 1024); } while (0)
; #define PG8_LDB(dst, b, h) do { _Pragma("unroll") for (int n = 0; n < 2; ++n) _Pragma("unroll") for (int k = 0; k < 2; ++k) dst[n][k] = *(const PG8_LAS bf16x8*)(lds + PG8_SB(b, h) + boff + n * 2048 + k * 1024); } while (0)
; #define PG8_MMA(ai, bj, At, Bt) do { __builtin_amdgcn_s_setprio(1); _Pragma("unroll") for (int m = 0; m < 4; ++m) _Pragma("unroll") for (int n = 0; n < 2; ++n) _Pragma("unroll") for (int k = 0; k < 2; ++k) \
;         acc[ai][bj][m][n] = __builtin_amdgcn_mfma_f32_16x16x32_bf16(Bt[n][k], At[m][k], acc[ai][bj][m][n], 0, 0, 0); __builtin_amdgcn_s_setprio(0); } while (0)
; #define PG8_WAIT_V(n) asm volatile("s_waitcnt vmcnt(" #n ")" ::: "memory")
; #define PG8_WAIT_L(n) asm volatile("s_waitcnt lgkmcnt(" #n ")" ::: "memory")
; #define PG8_BAR __builtin_amdgcn_s_barrier()
; #define PG8_SCHED __builtin_amdgcn_sched_barrier(0)
; template <class Epi, class Sched, bool ALIGN_EPI = false, bool SP2 = false, bool UNIFORM_NT = false>
; __device__ __forceinline__ void gemm_phase(PG8_LAS unsigned char* lds, const Gemm g, const Sched& S, const Epi& E, int tid_in) {
;     ...
;             PG8_WAIT_V(8); PG8_WAIT_L(0); PG8_BAR; PG8_MMA(1, 0, At, B0); PG8_MMA(1, 1, At, B1); PG8_BAR; PG8_SCHED;
;             PG8_LDB(B0, 1, 0); PG8_LDB(B1, 1, 1); PG8_SCHED; PG8_LDA(At, 1, 0); PG8_STAGE(PG8_SA(0, 1), a2 + hstepA, voffA);
;             PG8_WAIT_V(8); PG8_WAIT_L(0); PG8_BAR; PG8_MMA(0, 0, At, B0); PG8_MMA(0, 1, At, B1); PG8_BAR; PG8_SCHED;
	s_setprio 1
	s_waitcnt lgkmcnt(0)
	v_mfma_f32_16x16x32_bf16 v[62:65], v[140:143], v[190:193], v[62:65]
	v_mfma_f32_16x16x32_bf16 v[58:61], v[152:155], v[190:193], v[58:61]
	v_mfma_f32_16x16x32_bf16 v[54:57], v[140:143], v[198:201], v[54:57]
	v_mfma_f32_16x16x32_bf16 v[46:49], v[152:155], v[198:201], v[46:49]
	v_mfma_f32_16x16x32_bf16 v[38:41], v[140:143], v[206:209], v[38:41]
	v_mfma_f32_16x16x32_bf16 v[30:33], v[152:155], v[206:209], v[30:33]
	v_mfma_f32_16x16x32_bf16 v[22:25], v[140:143], v[214:217], v[22:25]
	v_mfma_f32_16x16x32_bf16 v[14:17], v[152:155], v[214:217], v[14:17]
	v_mfma_f32_16x16x32_bf16 v[62:65], v[148:151], v[194:197], v[62:65]
	v_mfma_f32_16x16x32_bf16 v[58:61], v[156:159], v[194:197], v[58:61]
	v_mfma_f32_16x16x32_bf16 v[54:57], v[148:151], v[202:205], v[54:57]
	v_mfma_f32_16x16x32_bf16 v[46:49], v[156:159], v[202:205], v[46:49]
	v_mfma_f32_16x16x32_bf16 v[38:41], v[148:151], v[210:213], v[38:41]
	v_mfma_f32_16x16x32_bf16 v[30:33], v[156:159], v[210:213], v[30:33]
	v_mfma_f32_16x16x32_bf16 v[22:25], v[148:151], v[218:221], v[22:25]
	v_mfma_f32_16x16x32_bf16 v[14:17], v[156:159], v[218:221], v[14:17]
	s_setprio 0
	s_setprio 1
	v_mfma_f32_16x16x32_bf16 v[50:53], v[160:163], v[190:193], v[50:53]
	v_mfma_f32_16x16x32_bf16 v[42:45], v[182:185], v[190:193], v[42:45]
	v_mfma_f32_16x16x32_bf16 v[34:37], v[160:163], v[198:201], v[34:37]
	v_mfma_f32_16x16x32_bf16 v[26:29], v[182:185], v[198:201], v[26:29]
	v_mfma_f32_16x16x32_bf16 v[18:21], v[160:163], v[206:209], v[18:21]
	v_mfma_f32_16x16x32_bf16 v[10:13], v[182:185], v[206:209], v[10:13]
	v_mfma_f32_16x16x32_bf16 v[6:9], v[160:163], v[214:217], v[6:9]
	v_mfma_f32_16x16x32_bf16 v[2:5], v[182:185], v[214:217], v[2:5]
	v_mfma_f32_16x16x32_bf16 v[50:53], v[178:181], v[194:197], v[50:53]
	v_mfma_f32_16x16x32_bf16 v[42:45], v[186:189], v[194:197], v[42:45]
	v_mfma_f32_16x16x32_bf16 v[34:37], v[178:181], v[202:205], v[34:37]
	v_mfma_f32_16x16x32_bf16 v[26:29], v[186:189], v[202:205], v[26:29]
	v_mfma_f32_16x16x32_bf16 v[18:21], v[178:181], v[210:213], v[18:21]
	v_mfma_f32_16x16x32_bf16 v[10:13], v[186:189], v[210:213], v[10:13]
	v_mfma_f32_16x16x32_bf16 v[6:9], v[178:181], v[218:221], v[6:9]
	v_mfma_f32_16x16x32_bf16 v[2:5], v[186:189], v[218:221], v[2:5]
	s_setprio 0
	s_barrier
	s_add_i32 s40, 0, 0x18000
	s_add_i32 s41, 0, 0x1c000
	v_add_u32_e32 v156, s40, v145
	v_add_u32_e32 v172, s41, v145
	ds_read_b128 v[140:143], v156
	ds_read_b128 v[148:151], v156 offset:1024
	ds_read_b128 v[152:155], v156 offset:2048
	ds_read_b128 v[156:159], v156 offset:3072
	ds_read_b128 v[160:163], v172
	ds_read_b128 v[178:181], v172 offset:1024
	ds_read_b128 v[182:185], v172 offset:2048
	ds_read_b128 v[186:189], v172 offset:3072
	s_add_u32 s28, s28, 0x40000
	s_addc_u32 s29, s29, 0
	s_mov_b32 m0, s14
	v_lshl_add_u64 v[172:173], s[28:29], 0, v[134:135]
	ds_read_b128 v[190:193], v147 offset:32768
	ds_read_b128 v[194:197], v147 offset:33792
	ds_read_b128 v[198:201], v147 offset:34816
	ds_read_b128 v[202:205], v147 offset:35840
	ds_read_b128 v[206:209], v147 offset:36864
	ds_read_b128 v[210:213], v147 offset:37888
	ds_read_b128 v[214:217], v147 offset:38912
	ds_read_b128 v[218:221], v147 offset:39936
	global_load_lds_dwordx4 v[172:173], off
	v_lshl_add_u64 v[172:173], s[28:29], 0, v[132:133]
	s_mov_b32 m0, s15
	s_nop 0
	global_load_lds_dwordx4 v[172:173], off
	s_waitcnt vmcnt(8)
	s_waitcnt lgkmcnt(0)
	s_barrier
	s_setprio 1
	s_waitcnt lgkmcnt(0)
	v_mfma_f32_16x16x32_bf16 v[126:129], v[140:143], v[190:193], v[126:129]
	v_mfma_f32_16x16x32_bf16 v[122:125], v[152:155], v[190:193], v[122:125]
	v_mfma_f32_16x16x32_bf16 v[118:121], v[140:143], v[198:201], v[118:121]
	v_mfma_f32_16x16x32_bf16 v[110:113], v[152:155], v[198:201], v[110:113]
	v_mfma_f32_16x16x32_bf16 v[102:105], v[140:143], v[206:209], v[102:105]
	v_mfma_f32_16x16x32_bf16 v[94:97], v[152:155], v[206:209], v[94:97]
	v_mfma_f32_16x16x32_bf16 v[86:89], v[140:143], v[214:217], v[86:89]
	v_mfma_f32_16x16x32_bf16 v[78:81], v[152:155], v[214:217], v[78:81]
	v_mfma_f32_16x16x32_bf16 v[126:129], v[148:151], v[194:197], v[126:129]
	v_mfma_f32_16x16x32_bf16 v[122:125], v[156:159], v[194:197], v[122:125]
	v_mfma_f32_16x16x32_bf16 v[118:121], v[148:151], v[202:205], v[118:121]
	v_mfma_f32_16x16x32_bf16 v[110:113], v[156:159], v[202:205], v[110:113]
	v_mfma_f32_16x16x32_bf16 v[102:105], v[148:151], v[210:213], v[102:105]
	v_mfma_f32_16x16x32_bf16 v[94:97], v[156:159], v[210:213], v[94:97]
	v_mfma_f32_16x16x32_bf16 v[86:89], v[148:151], v[218:221], v[86:89]
	v_mfma_f32_16x16x32_bf16 v[78:81], v[156:159], v[218:221], v[78:81]
	s_setprio 0
	s_setprio 1
	v_mfma_f32_16x16x32_bf16 v[114:117], v[160:163], v[190:193], v[114:117]
	v_mfma_f32_16x16x32_bf16 v[106:109], v[182:185], v[190:193], v[106:109]
	v_mfma_f32_16x16x32_bf16 v[98:101], v[160:163], v[198:201], v[98:101]
	v_mfma_f32_16x16x32_bf16 v[90:93], v[182:185], v[198:201], v[90:93]
	v_mfma_f32_16x16x32_bf16 v[82:85], v[160:163], v[206:209], v[82:85]
	v_mfma_f32_16x16x32_bf16 v[74:77], v[182:185], v[206:209], v[74:77]
	v_mfma_f32_16x16x32_bf16 v[70:73], v[160:163], v[214:217], v[70:73]
	v_mfma_f32_16x16x32_bf16 v[66:69], v[182:185], v[214:217], v[66:69]
	v_mfma_f32_16x16x32_bf16 v[114:117], v[178:181], v[194:197], v[114:117]
	v_mfma_f32_16x16x32_bf16 v[106:109], v[186:189], v[194:197], v[106:109]
	v_mfma_f32_16x16x32_bf16 v[98:101], v[178:181], v[202:205], v[98:101]
	v_mfma_f32_16x16x32_bf16 v[90:93], v[186:189], v[202:205], v[90:93]
	v_mfma_f32_16x16x32_bf16 v[82:85], v[178:181], v[210:213], v[82:85]
	v_mfma_f32_16x16x32_bf16 v[74:77], v[186:189], v[210:213], v[74:77]
	v_mfma_f32_16x16x32_bf16 v[70:73], v[178:181], v[218:221], v[70:73]
	v_mfma_f32_16x16x32_bf16 v[66:69], v[186:189], v[218:221], v[66:69]
	s_setprio 0
	s_barrier
; #define PG8_STAGE(bufoff, gbase, voff) do { _Pragma("unroll") for (int _i = 0; _i < 2; ++_i) \
;         __builtin_amdgcn_global_load_lds((const unsigned*)((const char*)(gbase) + (voff)[_i]), (PG8_LAS unsigned*)(lds + (bufoff) + ldsw + _i * 8192), 16, 0, 0); } while (0)
; #define PG8_LDA(dst, b, h) do { _Pragma("unroll") for (int m = 0; m < 4; ++m) _Pragma("unroll") for (int k = 0; k < 2; ++k) dst[m][k] = *(const PG8_LAS bf16x8*)(lds + PG8_SA(b, h) + aoff + m * 2048 + k * 1024); } while (0)
; #define PG8_MMA(ai, bj, At, Bt) do { __builtin_amdgcn_s_setprio(1); _Pragma("unroll") for (int m = 0; m < 4; ++m) _Pragma("unroll") for (int n = 0; n < 2; ++n) _Pragma("unroll") for (int k = 0; k < 2; ++k) \
;         acc[ai][bj][m][n] = __builtin_amdgcn_mfma_f32_16x16x32_bf16(Bt[n][k], At[m][k], acc[ai][bj][m][n], 0, 0, 0); __builtin_amdgcn_s_setprio(0); } while (0)
; #define PG8_WAIT_V(n) asm volatile("s_waitcnt vmcnt(" #n ")" ::: "memory")
; #define PG8_WAIT_L(n) asm volatile("s_waitcnt lgkmcnt(" #n ")" ::: "memory")
; #define PG8_BAR __builtin_amdgcn_s_barrier()
; #define PG8_SCHED __builtin_amdgcn_sched_barrier(0)
; template <class Epi, class Sched, bool ALIGN_EPI = false, bool SP2 = false, bool UNIFORM_NT = false>
; __device__ __forceinline__ void gemm_phase(PG8_LAS unsigned char* lds, const Gemm g, const Sched& S, const Epi& E, int tid_in) {
;     ...
;             PG8_LDA(At, 1, 1); PG8_STAGE(PG8_SB(1, 0), b3, voffB); PG8_STAGE(PG8_SB(1, 1), b3 + hstepB, voffB); PG8_STAGE(PG8_SA(1, 0), a3, voffA);
;             PG8_WAIT_V(8); PG8_WAIT_L(0); PG8_BAR; PG8_MMA(1, 0, At, B0); PG8_MMA(1, 1, At, B1); PG8_BAR; PG8_SCHED;
	s_add_i32 s28, s40, s3
	v_lshl_add_u64 v[164:165], v[164:165], 0, s[82:83]
	s_mov_b32 m0, s28
	ds_read_b128 v[190:193], v147 offset:49152
	ds_read_b128 v[194:197], v147 offset:50176
	ds_read_b128 v[198:201], v147 offset:51200
	ds_read_b128 v[202:205], v147 offset:52224
	ds_read_b128 v[206:209], v147 offset:53248
	ds_read_b128 v[210:213], v147 offset:54272
	ds_read_b128 v[214:217], v147 offset:55296
	ds_read_b128 v[218:221], v147 offset:56320
	global_load_lds_dwordx4 v[164:165], off
	s_add_i32 m0, s28, 0x2000
	s_add_u32 s26, s26, 0x40080
	v_lshl_add_u64 v[164:165], v[166:167], 0, s[82:83]
	s_addc_u32 s27, s27, 0
	s_add_i32 s28, s41, s3
	global_load_lds_dwordx4 v[164:165], off
	v_lshl_add_u64 v[164:165], s[26:27], 0, v[0:1]
	s_mov_b32 m0, s28
	s_nop 0
	global_load_lds_dwordx4 v[164:165], off
	v_lshl_add_u64 v[164:165], s[26:27], 0, v[130:131]
	s_add_i32 m0, s28, 0x2000
	s_nop 0
	global_load_lds_dwordx4 v[164:165], off
	v_lshl_add_u64 v[164:165], v[168:169], 0, s[82:83]
	s_mov_b32 m0, s30
	s_nop 0
	global_load_lds_dwordx4 v[164:165], off
	v_lshl_add_u64 v[164:165], v[170:171], 0, s[82:83]
	s_mov_b32 m0, s31
	s_nop 0
	global_load_lds_dwordx4 v[164:165], off
	s_waitcnt vmcnt(8)
	s_waitcnt lgkmcnt(0)
	s_barrier
	s_setprio 1
	s_waitcnt lgkmcnt(0)
	v_mfma_f32_16x16x32_bf16 v[62:65], v[140:143], v[190:193], v[62:65]
	v_mfma_f32_16x16x32_bf16 v[58:61], v[152:155], v[190:193], v[58:61]
	v_mfma_f32_16x16x32_bf16 v[54:57], v[140:143], v[198:201], v[54:57]
	v_mfma_f32_16x16x32_bf16 v[46:49], v[152:155], v[198:201], v[46:49]
	v_mfma_f32_16x16x32_bf16 v[38:41], v[140:143], v[206:209], v[38:41]
	v_mfma_f32_16x16x32_bf16 v[30:33], v[152:155], v[206:209], v[30:33]
	v_mfma_f32_16x16x32_bf16 v[22:25], v[140:143], v[214:217], v[22:25]
	v_mfma_f32_16x16x32_bf16 v[14:17], v[152:155], v[214:217], v[14:17]
	v_mfma_f32_16x16x32_bf16 v[62:65], v[148:151], v[194:197], v[62:65]
	v_mfma_f32_16x16x32_bf16 v[58:61], v[156:159], v[194:197], v[58:61]
	v_mfma_f32_16x16x32_bf16 v[54:57], v[148:151], v[202:205], v[54:57]
	v_mfma_f32_16x16x32_bf16 v[46:49], v[156:159], v[202:205], v[46:49]
	v_mfma_f32_16x16x32_bf16 v[38:41], v[148:151], v[210:213], v[38:41]
	v_mfma_f32_16x16x32_bf16 v[30:33], v[156:159], v[210:213], v[30:33]
	v_mfma_f32_16x16x32_bf16 v[22:25], v[148:151], v[218:221], v[22:25]
	v_mfma_f32_16x16x32_bf16 v[14:17], v[156:159], v[218:221], v[14:17]
	s_setprio 0
	s_setprio 1
	v_mfma_f32_16x16x32_bf16 v[50:53], v[160:163], v[190:193], v[50:53]
	v_mfma_f32_16x16x32_bf16 v[42:45], v[182:185], v[190:193], v[42:45]
	v_mfma_f32_16x16x32_bf16 v[34:37], v[160:163], v[198:201], v[34:37]
	v_mfma_f32_16x16x32_bf16 v[26:29], v[182:185], v[198:201], v[26:29]
	v_mfma_f32_16x16x32_bf16 v[18:21], v[160:163], v[206:209], v[18:21]
	v_mfma_f32_16x16x32_bf16 v[10:13], v[182:185], v[206:209], v[10:13]
	v_mfma_f32_16x16x32_bf16 v[6:9], v[160:163], v[214:217], v[6:9]
	v_mfma_f32_16x16x32_bf16 v[2:5], v[182:185], v[214:217], v[2:5]
	v_mfma_f32_16x16x32_bf16 v[50:53], v[178:181], v[194:197], v[50:53]
	v_mfma_f32_16x16x32_bf16 v[42:45], v[186:189], v[194:197], v[42:45]
	v_mfma_f32_16x16x32_bf16 v[34:37], v[178:181], v[202:205], v[34:37]
	v_mfma_f32_16x16x32_bf16 v[26:29], v[186:189], v[202:205], v[26:29]
	v_mfma_f32_16x16x32_bf16 v[18:21], v[178:181], v[210:213], v[18:21]
	v_mfma_f32_16x16x32_bf16 v[10:13], v[186:189], v[210:213], v[10:13]
	v_mfma_f32_16x16x32_bf16 v[6:9], v[178:181], v[218:221], v[6:9]
	v_mfma_f32_16x16x32_bf16 v[2:5], v[186:189], v[218:221], v[2:5]
	s_setprio 0
	s_barrier
	s_add_i32 s37, s37, 2
	s_add_u32 s24, s24, 0x100
	s_addc_u32 s25, s25, 0
	s_add_u32 s35, s35, 0x100
	s_addc_u32 s36, s36, 0
	s_cmp_gt_u32 s37, 13
	s_cbranch_scc0 .LBB0_833
	s_and_b64 vcc, exec, s[4:5]
	s_cbranch_vccz .LBB0_836
	s_barrier
